# ctx_finish (4-slice): chunks 2-4 issue their eight loads together, one wait per chunk instead of a wait after every load
# speedup vs baseline: 1.0008x; 1.0008x over previous
.LBB0_785:
	v_lshl_add_u64 v[56:57], v[30:31], 0, v[6:7]
	v_add_u32_e32 v0, 0x8000, v4
	v_add_co_u32_e32 v38, vcc, 0x1be00000, v56
	s_waitcnt lgkmcnt(0)
	v_ashrrev_i32_e32 v1, 31, v0
	v_addc_co_u32_e32 v39, vcc, 0, v57, vcc
	v_lshlrev_b64 v[54:55], 11, v[0:1]
	global_load_dwordx4 v[0:3], v[38:39], off
	v_add_co_u32_e32 v40, vcc, 0x1c600000, v56
	v_lshl_add_u64 v[42:43], v[32:33], 0, v[6:7]
	s_nop 0
	v_addc_co_u32_e32 v41, vcc, 0, v57, vcc
	v_add_co_u32_e32 v44, vcc, 0x1ce00000, v56
	s_waitcnt vmcnt(0)
	v_pk_add_f32 v[34:35], v[2:3], 0 op_sel_hi:[1,0]
	v_pk_add_f32 v[36:37], v[0:1], 0 op_sel_hi:[1,0]
	global_load_dwordx4 v[0:3], v[40:41], off
	v_addc_co_u32_e32 v45, vcc, 0, v57, vcc
	v_add_co_u32_e32 v46, vcc, 0x1d600000, v56
	s_waitcnt vmcnt(0)
	v_pk_add_f32 v[34:35], v[34:35], v[2:3]
	v_pk_add_f32 v[36:37], v[36:37], v[0:1]
	global_load_dwordx4 v[0:3], v[44:45], off
	v_addc_co_u32_e32 v47, vcc, 0, v57, vcc
	s_waitcnt vmcnt(0)
	v_pk_add_f32 v[34:35], v[34:35], v[2:3]
	v_pk_add_f32 v[36:37], v[36:37], v[0:1]
	global_load_dwordx4 v[0:3], v[46:47], off
	s_waitcnt vmcnt(0)
	v_pk_add_f32 v[58:59], v[34:35], v[2:3]
	v_pk_add_f32 v[60:61], v[36:37], v[0:1]
	global_load_dwordx4 v[0:3], v[42:43], off
	global_load_dwordx4 v[34:37], v[8:9], off
	s_waitcnt vmcnt(0)
	v_pk_fma_f32 v[0:1], v[60:61], v[34:35], v[0:1]
	v_add_co_u32_e32 v34, vcc, s86, v56
	v_pk_fma_f32 v[2:3], v[58:59], v[36:37], v[2:3]
	s_nop 0
	v_addc_co_u32_e32 v35, vcc, 0, v57, vcc
	global_store_dwordx4 v[34:35], v[0:3], off
	v_lshl_add_u64 v[36:37], v[26:27], 0, v[54:55]
	global_load_dwordx4 v[54:57], v[10:11], off
	global_load_dwordx4 v[58:61], v[12:13], off
	v_mul_f32_e32 v66, v1, v1
	v_fmac_f32_e32 v66, v0, v0
	v_mul_f32_e32 v5, v3, v3
	v_fmac_f32_e32 v5, v2, v2
	s_waitcnt vmcnt(0)
	v_pk_add_f32 v[60:61], v[60:61], 1.0 op_sel_hi:[1,0]
	v_pk_add_f32 v[58:59], v[58:59], 1.0 op_sel_hi:[1,0]
	v_pk_mul_f32 v[56:57], v[56:57], v[60:61]
	v_pk_mul_f32 v[54:55], v[54:55], v[58:59]
	v_pk_mul_f32 v[56:57], v[2:3], v[56:57]
	v_pk_mul_f32 v[54:55], v[0:1], v[54:55]
	s_nop 0
	v_cvt_pk_bf16_f32 v54, v54, v55
	v_cvt_pk_bf16_f32 v55, v56, v57
	global_store_dwordx2 v[36:37], v[54:55], off
	global_load_dwordx4 v[104:107], v[38:39], off offset:1024
	global_load_dwordx4 v[108:111], v[40:41], off offset:1024
	global_load_dwordx4 v[112:115], v[44:45], off offset:1024
	global_load_dwordx4 v[116:119], v[46:47], off offset:1024
	global_load_dwordx4 v[120:123], v[42:43], off offset:1024
	global_load_dwordx4 v[124:127], v[14:15], off
	global_load_dwordx4 v[128:131], v[10:11], off offset:1024
	global_load_dwordx4 v[132:135], v[16:17], off
	s_waitcnt vmcnt(0)
	v_mov_b64_e32 v[54:55], v[104:105]
	v_mov_b64_e32 v[56:57], v[106:107]
	v_pk_add_f32 v[58:59], v[56:57], 0 op_sel_hi:[1,0]
	v_pk_add_f32 v[60:61], v[54:55], 0 op_sel_hi:[1,0]
	v_mov_b64_e32 v[54:55], v[108:109]
	v_mov_b64_e32 v[56:57], v[110:111]
	v_pk_add_f32 v[58:59], v[58:59], v[56:57]
	v_pk_add_f32 v[60:61], v[60:61], v[54:55]
	v_mov_b64_e32 v[54:55], v[112:113]
	v_mov_b64_e32 v[56:57], v[114:115]
	v_pk_add_f32 v[58:59], v[58:59], v[56:57]
	v_pk_add_f32 v[60:61], v[60:61], v[54:55]
	v_mov_b64_e32 v[54:55], v[116:117]
	v_mov_b64_e32 v[56:57], v[118:119]
	v_pk_add_f32 v[62:63], v[58:59], v[56:57]
	v_pk_add_f32 v[64:65], v[60:61], v[54:55]
	v_mov_b64_e32 v[54:55], v[120:121]
	v_mov_b64_e32 v[56:57], v[122:123]
	v_mov_b64_e32 v[58:59], v[124:125]
	v_mov_b64_e32 v[60:61], v[126:127]
	v_pk_fma_f32 v[56:57], v[62:63], v[60:61], v[56:57]
	v_pk_fma_f32 v[54:55], v[64:65], v[58:59], v[54:55]
	global_store_dwordx4 v[34:35], v[54:57], off offset:1024
	v_mov_b64_e32 v[58:59], v[128:129]
	v_mov_b64_e32 v[60:61], v[130:131]
	v_mov_b64_e32 v[62:63], v[132:133]
	v_mov_b64_e32 v[64:65], v[134:135]
	v_mul_f32_e32 v67, v57, v57
	v_fmac_f32_e32 v67, v56, v56
	v_mul_f32_e32 v3, v55, v55
	v_fmac_f32_e32 v3, v54, v54
	v_pk_add_f32 v[0:1], v[64:65], 1.0 op_sel_hi:[1,0]
	v_pk_add_f32 v[62:63], v[62:63], 1.0 op_sel_hi:[1,0]
	v_pk_mul_f32 v[0:1], v[60:61], v[0:1]
	v_pk_mul_f32 v[58:59], v[58:59], v[62:63]
	v_pk_mul_f32 v[0:1], v[56:57], v[0:1]
	v_pk_mul_f32 v[56:57], v[54:55], v[58:59]
	v_add_f32_e32 v62, v3, v67
	v_cvt_pk_bf16_f32 v56, v56, v57
	v_cvt_pk_bf16_f32 v57, v0, v1
	global_store_dwordx2 v[36:37], v[56:57], off offset:512
	global_load_dwordx4 v[104:107], v[38:39], off offset:2048
	global_load_dwordx4 v[108:111], v[40:41], off offset:2048
	global_load_dwordx4 v[112:115], v[44:45], off offset:2048
	global_load_dwordx4 v[116:119], v[46:47], off offset:2048
	global_load_dwordx4 v[120:123], v[42:43], off offset:2048
	global_load_dwordx4 v[124:127], v[18:19], off
	global_load_dwordx4 v[128:131], v[10:11], off offset:2048
	global_load_dwordx4 v[132:135], v[20:21], off
	s_waitcnt vmcnt(0)
	v_mov_b64_e32 v[56:57], v[104:105]
	v_mov_b64_e32 v[58:59], v[106:107]
	v_pk_add_f32 v[0:1], v[58:59], 0 op_sel_hi:[1,0]
	v_pk_add_f32 v[60:61], v[56:57], 0 op_sel_hi:[1,0]
	v_mov_b64_e32 v[56:57], v[108:109]
	v_mov_b64_e32 v[58:59], v[110:111]
	v_pk_add_f32 v[0:1], v[0:1], v[58:59]
	v_pk_add_f32 v[60:61], v[60:61], v[56:57]
	v_mov_b64_e32 v[56:57], v[112:113]
	v_mov_b64_e32 v[58:59], v[114:115]
	v_pk_add_f32 v[0:1], v[0:1], v[58:59]
	v_pk_add_f32 v[60:61], v[60:61], v[56:57]
	v_mov_b64_e32 v[56:57], v[116:117]
	v_mov_b64_e32 v[58:59], v[118:119]
	v_pk_add_f32 v[58:59], v[0:1], v[58:59]
	v_pk_add_f32 v[60:61], v[60:61], v[56:57]
	v_mov_b64_e32 v[0:1], v[120:121]
	v_mov_b64_e32 v[2:3], v[122:123]
	v_mov_b64_e32 v[54:55], v[124:125]
	v_mov_b64_e32 v[56:57], v[126:127]
	v_pk_fma_f32 v[2:3], v[58:59], v[56:57], v[2:3]
	v_pk_fma_f32 v[0:1], v[60:61], v[54:55], v[0:1]
	global_store_dwordx4 v[34:35], v[0:3], off offset:2048
	v_mov_b64_e32 v[54:55], v[128:129]
	v_mov_b64_e32 v[56:57], v[130:131]
	v_mov_b64_e32 v[58:59], v[132:133]
	v_mov_b64_e32 v[60:61], v[134:135]
	v_mul_f32_e32 v64, v3, v3
	v_fmac_f32_e32 v64, v2, v2
	v_mul_f32_e32 v63, v1, v1
	v_fmac_f32_e32 v63, v0, v0
	v_pk_add_f32 v[60:61], v[60:61], 1.0 op_sel_hi:[1,0]
	v_pk_add_f32 v[58:59], v[58:59], 1.0 op_sel_hi:[1,0]
	v_pk_mul_f32 v[56:57], v[56:57], v[60:61]
	v_pk_mul_f32 v[54:55], v[54:55], v[58:59]
	v_pk_mul_f32 v[2:3], v[2:3], v[56:57]
	v_pk_mul_f32 v[54:55], v[0:1], v[54:55]
	v_add_f32_e32 v1, v66, v5
	v_cvt_pk_bf16_f32 v54, v54, v55
	v_cvt_pk_bf16_f32 v55, v2, v3
	global_store_dwordx2 v[36:37], v[54:55], off offset:1024
	global_load_dwordx4 v[104:107], v[38:39], off offset:3072
	global_load_dwordx4 v[108:111], v[40:41], off offset:3072
	global_load_dwordx4 v[112:115], v[44:45], off offset:3072
	global_load_dwordx4 v[116:119], v[46:47], off offset:3072
	global_load_dwordx4 v[120:123], v[42:43], off offset:3072
	global_load_dwordx4 v[124:127], v[22:23], off
	global_load_dwordx4 v[128:131], v[10:11], off offset:3072
	global_load_dwordx4 v[132:135], v[24:25], off
	s_waitcnt vmcnt(0)
	v_mov_b64_e32 v[54:55], v[104:105]
	v_mov_b64_e32 v[56:57], v[106:107]
	v_add_f32_e32 v1, v1, v62
	v_mov_b64_e32 v[38:39], v[108:109]
	v_mov_b64_e32 v[40:41], v[110:111]
	v_add_f32_e32 v0, v63, v64
	v_add_f32_e32 v5, v1, v0
	v_pk_add_f32 v[2:3], v[56:57], 0 op_sel_hi:[1,0]
	v_pk_add_f32 v[54:55], v[54:55], 0 op_sel_hi:[1,0]
	v_pk_add_f32 v[2:3], v[2:3], v[40:41]
	v_pk_add_f32 v[54:55], v[54:55], v[38:39]
	v_mov_b64_e32 v[38:39], v[112:113]
	v_mov_b64_e32 v[40:41], v[114:115]
	v_pk_add_f32 v[2:3], v[2:3], v[40:41]
	v_pk_add_f32 v[44:45], v[54:55], v[38:39]
	v_mov_b64_e32 v[38:39], v[116:117]
	v_mov_b64_e32 v[40:41], v[118:119]
	v_pk_add_f32 v[46:47], v[2:3], v[40:41]
	v_pk_add_f32 v[44:45], v[44:45], v[38:39]
	v_mov_b64_e32 v[0:1], v[120:121]
	v_mov_b64_e32 v[2:3], v[122:123]
	v_mov_b64_e32 v[38:39], v[124:125]
	v_mov_b64_e32 v[40:41], v[126:127]
	v_pk_fma_f32 v[2:3], v[46:47], v[40:41], v[2:3]
	v_pk_fma_f32 v[0:1], v[44:45], v[38:39], v[0:1]
	global_store_dwordx4 v[34:35], v[0:3], off offset:3072
	v_mov_b64_e32 v[38:39], v[128:129]
	v_mov_b64_e32 v[40:41], v[130:131]
	v_mov_b64_e32 v[42:43], v[132:133]
	v_mov_b64_e32 v[44:45], v[134:135]
	v_mul_f32_e32 v34, v1, v1
	v_mul_f32_e32 v35, v3, v3
	v_fmac_f32_e32 v34, v0, v0
	v_fmac_f32_e32 v35, v2, v2
	v_add_f32_e32 v34, v34, v35
	v_add_f32_e32 v5, v5, v34
	v_pk_add_f32 v[34:35], v[44:45], 1.0 op_sel_hi:[1,0]
	v_pk_add_f32 v[42:43], v[42:43], 1.0 op_sel_hi:[1,0]
	v_pk_mul_f32 v[34:35], v[40:41], v[34:35]
	v_pk_mul_f32 v[38:39], v[38:39], v[42:43]
	v_pk_mul_f32 v[2:3], v[2:3], v[34:35]
	v_pk_mul_f32 v[0:1], v[0:1], v[38:39]
	s_nop 0
	v_cvt_pk_bf16_f32 v0, v0, v1
	v_cvt_pk_bf16_f32 v1, v2, v3
	global_store_dwordx2 v[36:37], v[0:1], off offset:1536
	ds_bpermute_b32 v0, v48, v5
	s_waitcnt lgkmcnt(0)
	v_add_f32_e32 v0, v5, v0
	ds_bpermute_b32 v1, v49, v0
	s_waitcnt lgkmcnt(0)
	v_add_f32_e32 v0, v0, v1
	ds_bpermute_b32 v1, v50, v0
	s_waitcnt lgkmcnt(0)
	v_add_f32_e32 v0, v0, v1
	ds_bpermute_b32 v1, v51, v0
	s_waitcnt lgkmcnt(0)
	v_add_f32_e32 v0, v0, v1
	ds_bpermute_b32 v1, v52, v0
	s_waitcnt lgkmcnt(0)
	v_add_f32_e32 v0, v0, v1
	ds_bpermute_b32 v1, v53, v0
	s_and_saveexec_b64 s[16:17], s[40:41]
	s_cbranch_execz .LBB0_784
	s_waitcnt lgkmcnt(0)
	v_add_f32_e32 v0, v0, v1
	flat_store_dword v[28:29], v0
	s_branch .LBB0_784
